# nt hint also on the SwiGLU hidden (H) stores of the ffn-in epilogue
# baseline (speedup 1.0000x reference)
.LBB0_1125:
	s_lshl_b32 s12, s28, 8
	s_add_i32 s12, s12, s51
	v_or_b32_e32 v148, s12, v139
	v_ashrrev_i32_e32 v149, 31, v148
	v_lshl_add_u64 v[172:173], v[148:149], 2, s[8:9]
	global_load_dword v230, v[172:173], off
	global_load_dword v231, v[172:173], off offset:64
	global_load_dword v232, v[172:173], off offset:128
	global_load_dword v233, v[172:173], off offset:192
	global_load_dword v234, v[172:173], off offset:512
	global_load_dword v235, v[172:173], off offset:576
	global_load_dword v236, v[172:173], off offset:640
	global_load_dword v237, v[172:173], off offset:704
	s_ashr_i32 s13, s12, 13
	s_mul_i32 s40, s13, 0x1600
	s_lshl_b32 s36, s29, 8
	s_lshl_b32 s28, s29, 7
	s_ashr_i32 s41, s40, 31
	s_ashr_i32 s37, s36, 31
	s_ashr_i32 s29, s28, 31
	s_lshl_b64 s[40:41], s[40:41], 2
	s_add_u32 s13, s52, s40
	s_addc_u32 s21, s53, s41
	s_lshl_b64 s[36:37], s[36:37], 2
	s_add_u32 s40, s13, s36
	s_addc_u32 s41, s21, s37
	v_lshlrev_b32_e32 v149, 2, v138
	global_load_dwordx4 v[160:163], v149, s[40:41]
	global_load_dwordx4 v[156:159], v149, s[40:41] offset:512
	global_load_dwordx4 v[168:171], v149, s[40:41] offset:16
	global_load_dwordx4 v[164:167], v149, s[40:41] offset:528
	s_lshl_b64 s[28:29], s[28:29], 1
	s_mov_b32 s98, 0x16000
	s_mov_b32 s99, 0
	s_mov_b32 s100, 0x6e000
	s_mov_b32 s101, 0
	v_mov_b64_e32 v[174:175], s[92:93]
	v_lshlrev_b32_e32 v136, 1, v138
	v_mad_i64_i32 v[246:247], s[44:45], v148, s59, v[174:175]
	v_lshl_add_u64 v[246:247], v[246:247], 0, s[28:29]
	v_lshl_add_u64 v[246:247], v[246:247], 0, v[136:137]
	s_waitcnt vmcnt(0)
	v_fmamk_f32 v230, v230, 0x3a800000, v154
	v_fmamk_f32 v231, v231, 0x3a800000, v154
	v_fmamk_f32 v232, v232, 0x3a800000, v154
	v_fmamk_f32 v233, v233, 0x3a800000, v154
	v_fmamk_f32 v234, v234, 0x3a800000, v154
	v_fmamk_f32 v235, v235, 0x3a800000, v154
	v_fmamk_f32 v236, v236, 0x3a800000, v154
	v_fmamk_f32 v237, v237, 0x3a800000, v154
	v_rsq_f32_e32 v230, v230
	v_rsq_f32_e32 v231, v231
	v_rsq_f32_e32 v232, v232
	v_rsq_f32_e32 v233, v233
	v_rsq_f32_e32 v234, v234
	v_rsq_f32_e32 v235, v235
	v_rsq_f32_e32 v236, v236
	v_rsq_f32_e32 v237, v237
	v_fma_f32 v124, v124, v230, v160
	v_fma_f32 v125, v125, v230, v161
	v_fma_f32 v126, v126, v230, v162
	v_fma_f32 v127, v127, v230, v163
	v_fma_f32 v120, v120, v230, v168
	v_fma_f32 v121, v121, v230, v169
	v_fma_f32 v122, v122, v230, v170
	v_fma_f32 v123, v123, v230, v171
	v_mul_f32_e32 v238, 0xbfb8aa3b, v124
	v_mul_f32_e32 v239, 0xbfb8aa3b, v125
	v_mul_f32_e32 v240, 0xbfb8aa3b, v126
	v_mul_f32_e32 v241, 0xbfb8aa3b, v127
	v_mul_f32_e32 v242, 0xbfb8aa3b, v120
	v_mul_f32_e32 v243, 0xbfb8aa3b, v121
	v_mul_f32_e32 v244, 0xbfb8aa3b, v122
	v_mul_f32_e32 v245, 0xbfb8aa3b, v123
	v_exp_f32_e32 v238, v238
	v_exp_f32_e32 v239, v239
	v_exp_f32_e32 v240, v240
	v_exp_f32_e32 v241, v241
	v_exp_f32_e32 v242, v242
	v_exp_f32_e32 v243, v243
	v_exp_f32_e32 v244, v244
	v_exp_f32_e32 v245, v245
	v_fma_f32 v116, v116, v230, v156
	v_fma_f32 v117, v117, v230, v157
	v_fma_f32 v118, v118, v230, v158
	v_fma_f32 v119, v119, v230, v159
	v_fma_f32 v112, v112, v230, v164
	v_fma_f32 v113, v113, v230, v165
	v_fma_f32 v114, v114, v230, v166
	v_fma_f32 v115, v115, v230, v167
	v_add_f32_e32 v238, 1.0, v238
	v_add_f32_e32 v239, 1.0, v239
	v_add_f32_e32 v240, 1.0, v240
	v_add_f32_e32 v241, 1.0, v241
	v_add_f32_e32 v242, 1.0, v242
	v_add_f32_e32 v243, 1.0, v243
	v_add_f32_e32 v244, 1.0, v244
	v_add_f32_e32 v245, 1.0, v245
	v_rcp_f32_e32 v238, v238
	v_rcp_f32_e32 v239, v239
	v_rcp_f32_e32 v240, v240
	v_rcp_f32_e32 v241, v241
	v_rcp_f32_e32 v242, v242
	v_rcp_f32_e32 v243, v243
	v_rcp_f32_e32 v244, v244
	v_rcp_f32_e32 v245, v245
	v_mul_f32_e32 v124, v124, v116
	v_mul_f32_e32 v125, v125, v117
	v_mul_f32_e32 v126, v126, v118
	v_mul_f32_e32 v127, v127, v119
	v_mul_f32_e32 v120, v120, v112
	v_mul_f32_e32 v121, v121, v113
	v_mul_f32_e32 v122, v122, v114
	v_mul_f32_e32 v123, v123, v115
	v_mul_f32_e32 v124, v124, v238
	v_mul_f32_e32 v125, v125, v239
	v_mul_f32_e32 v126, v126, v240
	v_mul_f32_e32 v127, v127, v241
	v_mul_f32_e32 v120, v120, v242
	v_mul_f32_e32 v121, v121, v243
	v_mul_f32_e32 v122, v122, v244
	v_mul_f32_e32 v123, v123, v245
	v_cvt_pk_bf16_f32 v112, v124, v125
	v_cvt_pk_bf16_f32 v113, v126, v127
	v_cvt_pk_bf16_f32 v114, v120, v121
	v_cvt_pk_bf16_f32 v115, v122, v123
	global_store_dwordx4 v[246:247], v[112:115], off nt
	v_lshl_add_u64 v[246:247], v[246:247], 0, s[98:99]
	v_fma_f32 v108, v108, v231, v160
	v_fma_f32 v109, v109, v231, v161
	v_fma_f32 v110, v110, v231, v162
	v_fma_f32 v111, v111, v231, v163
	v_fma_f32 v104, v104, v231, v168
	v_fma_f32 v105, v105, v231, v169
	v_fma_f32 v106, v106, v231, v170
	v_fma_f32 v107, v107, v231, v171
	v_mul_f32_e32 v238, 0xbfb8aa3b, v108
	v_mul_f32_e32 v239, 0xbfb8aa3b, v109
	v_mul_f32_e32 v240, 0xbfb8aa3b, v110
	v_mul_f32_e32 v241, 0xbfb8aa3b, v111
	v_mul_f32_e32 v242, 0xbfb8aa3b, v104
	v_mul_f32_e32 v243, 0xbfb8aa3b, v105
	v_mul_f32_e32 v244, 0xbfb8aa3b, v106
	v_mul_f32_e32 v245, 0xbfb8aa3b, v107
	v_exp_f32_e32 v238, v238
	v_exp_f32_e32 v239, v239
	v_exp_f32_e32 v240, v240
	v_exp_f32_e32 v241, v241
	v_exp_f32_e32 v242, v242
	v_exp_f32_e32 v243, v243
	v_exp_f32_e32 v244, v244
	v_exp_f32_e32 v245, v245
	v_fma_f32 v100, v100, v231, v156
	v_fma_f32 v101, v101, v231, v157
	v_fma_f32 v102, v102, v231, v158
	v_fma_f32 v103, v103, v231, v159
	v_fma_f32 v96, v96, v231, v164
	v_fma_f32 v97, v97, v231, v165
	v_fma_f32 v98, v98, v231, v166
	v_fma_f32 v99, v99, v231, v167
	v_add_f32_e32 v238, 1.0, v238
	v_add_f32_e32 v239, 1.0, v239
	v_add_f32_e32 v240, 1.0, v240
	v_add_f32_e32 v241, 1.0, v241
	v_add_f32_e32 v242, 1.0, v242
	v_add_f32_e32 v243, 1.0, v243
	v_add_f32_e32 v244, 1.0, v244
	v_add_f32_e32 v245, 1.0, v245
	v_rcp_f32_e32 v238, v238
	v_rcp_f32_e32 v239, v239
	v_rcp_f32_e32 v240, v240
	v_rcp_f32_e32 v241, v241
	v_rcp_f32_e32 v242, v242
	v_rcp_f32_e32 v243, v243
	v_rcp_f32_e32 v244, v244
	v_rcp_f32_e32 v245, v245
	v_mul_f32_e32 v108, v108, v100
	v_mul_f32_e32 v109, v109, v101
	v_mul_f32_e32 v110, v110, v102
	v_mul_f32_e32 v111, v111, v103
	v_mul_f32_e32 v104, v104, v96
	v_mul_f32_e32 v105, v105, v97
	v_mul_f32_e32 v106, v106, v98
	v_mul_f32_e32 v107, v107, v99
	v_mul_f32_e32 v108, v108, v238
	v_mul_f32_e32 v109, v109, v239
	v_mul_f32_e32 v110, v110, v240
	v_mul_f32_e32 v111, v111, v241
	v_mul_f32_e32 v104, v104, v242
	v_mul_f32_e32 v105, v105, v243
	v_mul_f32_e32 v106, v106, v244
	v_mul_f32_e32 v107, v107, v245
	v_cvt_pk_bf16_f32 v96, v108, v109
	v_cvt_pk_bf16_f32 v97, v110, v111
	v_cvt_pk_bf16_f32 v98, v104, v105
	v_cvt_pk_bf16_f32 v99, v106, v107
	global_store_dwordx4 v[246:247], v[96:99], off nt
	v_lshl_add_u64 v[246:247], v[246:247], 0, s[98:99]
	v_fma_f32 v92, v92, v232, v160
	v_fma_f32 v93, v93, v232, v161
	v_fma_f32 v94, v94, v232, v162
	v_fma_f32 v95, v95, v232, v163
	v_fma_f32 v88, v88, v232, v168
	v_fma_f32 v89, v89, v232, v169
	v_fma_f32 v90, v90, v232, v170
	v_fma_f32 v91, v91, v232, v171
	v_mul_f32_e32 v238, 0xbfb8aa3b, v92
	v_mul_f32_e32 v239, 0xbfb8aa3b, v93
	v_mul_f32_e32 v240, 0xbfb8aa3b, v94
	v_mul_f32_e32 v241, 0xbfb8aa3b, v95
	v_mul_f32_e32 v242, 0xbfb8aa3b, v88
	v_mul_f32_e32 v243, 0xbfb8aa3b, v89
	v_mul_f32_e32 v244, 0xbfb8aa3b, v90
	v_mul_f32_e32 v245, 0xbfb8aa3b, v91
	v_exp_f32_e32 v238, v238
	v_exp_f32_e32 v239, v239
	v_exp_f32_e32 v240, v240
	v_exp_f32_e32 v241, v241
	v_exp_f32_e32 v242, v242
	v_exp_f32_e32 v243, v243
	v_exp_f32_e32 v244, v244
	v_exp_f32_e32 v245, v245
	v_fma_f32 v84, v84, v232, v156
	v_fma_f32 v85, v85, v232, v157
	v_fma_f32 v86, v86, v232, v158
	v_fma_f32 v87, v87, v232, v159
	v_fma_f32 v80, v80, v232, v164
	v_fma_f32 v81, v81, v232, v165
	v_fma_f32 v82, v82, v232, v166
	v_fma_f32 v83, v83, v232, v167
	v_add_f32_e32 v238, 1.0, v238
	v_add_f32_e32 v239, 1.0, v239
	v_add_f32_e32 v240, 1.0, v240
	v_add_f32_e32 v241, 1.0, v241
	v_add_f32_e32 v242, 1.0, v242
	v_add_f32_e32 v243, 1.0, v243
	v_add_f32_e32 v244, 1.0, v244
	v_add_f32_e32 v245, 1.0, v245
	v_rcp_f32_e32 v238, v238
	v_rcp_f32_e32 v239, v239
	v_rcp_f32_e32 v240, v240
	v_rcp_f32_e32 v241, v241
	v_rcp_f32_e32 v242, v242
	v_rcp_f32_e32 v243, v243
	v_rcp_f32_e32 v244, v244
	v_rcp_f32_e32 v245, v245
	v_mul_f32_e32 v92, v92, v84
	v_mul_f32_e32 v93, v93, v85
	v_mul_f32_e32 v94, v94, v86
	v_mul_f32_e32 v95, v95, v87
	v_mul_f32_e32 v88, v88, v80
	v_mul_f32_e32 v89, v89, v81
	v_mul_f32_e32 v90, v90, v82
	v_mul_f32_e32 v91, v91, v83
	v_mul_f32_e32 v92, v92, v238
	v_mul_f32_e32 v93, v93, v239
	v_mul_f32_e32 v94, v94, v240
	v_mul_f32_e32 v95, v95, v241
	v_mul_f32_e32 v88, v88, v242
	v_mul_f32_e32 v89, v89, v243
	v_mul_f32_e32 v90, v90, v244
	v_mul_f32_e32 v91, v91, v245
	v_cvt_pk_bf16_f32 v80, v92, v93
	v_cvt_pk_bf16_f32 v81, v94, v95
	v_cvt_pk_bf16_f32 v82, v88, v89
	v_cvt_pk_bf16_f32 v83, v90, v91
	global_store_dwordx4 v[246:247], v[80:83], off nt
	v_lshl_add_u64 v[246:247], v[246:247], 0, s[98:99]
	v_fma_f32 v76, v76, v233, v160
	v_fma_f32 v77, v77, v233, v161
	v_fma_f32 v78, v78, v233, v162
	v_fma_f32 v79, v79, v233, v163
	v_fma_f32 v72, v72, v233, v168
	v_fma_f32 v73, v73, v233, v169
	v_fma_f32 v74, v74, v233, v170
	v_fma_f32 v75, v75, v233, v171
	v_mul_f32_e32 v238, 0xbfb8aa3b, v76
	v_mul_f32_e32 v239, 0xbfb8aa3b, v77
	v_mul_f32_e32 v240, 0xbfb8aa3b, v78
	v_mul_f32_e32 v241, 0xbfb8aa3b, v79
	v_mul_f32_e32 v242, 0xbfb8aa3b, v72
	v_mul_f32_e32 v243, 0xbfb8aa3b, v73
	v_mul_f32_e32 v244, 0xbfb8aa3b, v74
	v_mul_f32_e32 v245, 0xbfb8aa3b, v75
	v_exp_f32_e32 v238, v238
	v_exp_f32_e32 v239, v239
	v_exp_f32_e32 v240, v240
	v_exp_f32_e32 v241, v241
	v_exp_f32_e32 v242, v242
	v_exp_f32_e32 v243, v243
	v_exp_f32_e32 v244, v244
	v_exp_f32_e32 v245, v245
	v_fma_f32 v68, v68, v233, v156
	v_fma_f32 v69, v69, v233, v157
	v_fma_f32 v70, v70, v233, v158
	v_fma_f32 v71, v71, v233, v159
	v_fma_f32 v64, v64, v233, v164
	v_fma_f32 v65, v65, v233, v165
	v_fma_f32 v66, v66, v233, v166
	v_fma_f32 v67, v67, v233, v167
	v_add_f32_e32 v238, 1.0, v238
	v_add_f32_e32 v239, 1.0, v239
	v_add_f32_e32 v240, 1.0, v240
	v_add_f32_e32 v241, 1.0, v241
	v_add_f32_e32 v242, 1.0, v242
	v_add_f32_e32 v243, 1.0, v243
	v_add_f32_e32 v244, 1.0, v244
	v_add_f32_e32 v245, 1.0, v245
	v_rcp_f32_e32 v238, v238
	v_rcp_f32_e32 v239, v239
	v_rcp_f32_e32 v240, v240
	v_rcp_f32_e32 v241, v241
	v_rcp_f32_e32 v242, v242
	v_rcp_f32_e32 v243, v243
	v_rcp_f32_e32 v244, v244
	v_rcp_f32_e32 v245, v245
	v_mul_f32_e32 v76, v76, v68
	v_mul_f32_e32 v77, v77, v69
	v_mul_f32_e32 v78, v78, v70
	v_mul_f32_e32 v79, v79, v71
	v_mul_f32_e32 v72, v72, v64
	v_mul_f32_e32 v73, v73, v65
	v_mul_f32_e32 v74, v74, v66
	v_mul_f32_e32 v75, v75, v67
	v_mul_f32_e32 v76, v76, v238
	v_mul_f32_e32 v77, v77, v239
	v_mul_f32_e32 v78, v78, v240
	v_mul_f32_e32 v79, v79, v241
	v_mul_f32_e32 v72, v72, v242
	v_mul_f32_e32 v73, v73, v243
	v_mul_f32_e32 v74, v74, v244
	v_mul_f32_e32 v75, v75, v245
	v_cvt_pk_bf16_f32 v64, v76, v77
	v_cvt_pk_bf16_f32 v65, v78, v79
	v_cvt_pk_bf16_f32 v66, v72, v73
	v_cvt_pk_bf16_f32 v67, v74, v75
	global_store_dwordx4 v[246:247], v[64:67], off nt
	v_lshl_add_u64 v[246:247], v[246:247], 0, s[100:101]
	v_fma_f32 v60, v60, v234, v160
	v_fma_f32 v61, v61, v234, v161
	v_fma_f32 v62, v62, v234, v162
	v_fma_f32 v63, v63, v234, v163
	v_fma_f32 v56, v56, v234, v168
	v_fma_f32 v57, v57, v234, v169
	v_fma_f32 v58, v58, v234, v170
	v_fma_f32 v59, v59, v234, v171
	v_mul_f32_e32 v238, 0xbfb8aa3b, v60
	v_mul_f32_e32 v239, 0xbfb8aa3b, v61
	v_mul_f32_e32 v240, 0xbfb8aa3b, v62
	v_mul_f32_e32 v241, 0xbfb8aa3b, v63
	v_mul_f32_e32 v242, 0xbfb8aa3b, v56
	v_mul_f32_e32 v243, 0xbfb8aa3b, v57
	v_mul_f32_e32 v244, 0xbfb8aa3b, v58
	v_mul_f32_e32 v245, 0xbfb8aa3b, v59
	v_exp_f32_e32 v238, v238
	v_exp_f32_e32 v239, v239
	v_exp_f32_e32 v240, v240
	v_exp_f32_e32 v241, v241
	v_exp_f32_e32 v242, v242
	v_exp_f32_e32 v243, v243
	v_exp_f32_e32 v244, v244
	v_exp_f32_e32 v245, v245
	v_fma_f32 v52, v52, v234, v156
	v_fma_f32 v53, v53, v234, v157
	v_fma_f32 v54, v54, v234, v158
	v_fma_f32 v55, v55, v234, v159
	v_fma_f32 v48, v48, v234, v164
	v_fma_f32 v49, v49, v234, v165
	v_fma_f32 v50, v50, v234, v166
	v_fma_f32 v51, v51, v234, v167
	v_add_f32_e32 v238, 1.0, v238
	v_add_f32_e32 v239, 1.0, v239
	v_add_f32_e32 v240, 1.0, v240
	v_add_f32_e32 v241, 1.0, v241
	v_add_f32_e32 v242, 1.0, v242
	v_add_f32_e32 v243, 1.0, v243
	v_add_f32_e32 v244, 1.0, v244
	v_add_f32_e32 v245, 1.0, v245
	v_rcp_f32_e32 v238, v238
	v_rcp_f32_e32 v239, v239
	v_rcp_f32_e32 v240, v240
	v_rcp_f32_e32 v241, v241
	v_rcp_f32_e32 v242, v242
	v_rcp_f32_e32 v243, v243
	v_rcp_f32_e32 v244, v244
	v_rcp_f32_e32 v245, v245
	v_mul_f32_e32 v60, v60, v52
	v_mul_f32_e32 v61, v61, v53
	v_mul_f32_e32 v62, v62, v54
	v_mul_f32_e32 v63, v63, v55
	v_mul_f32_e32 v56, v56, v48
	v_mul_f32_e32 v57, v57, v49
	v_mul_f32_e32 v58, v58, v50
	v_mul_f32_e32 v59, v59, v51
	v_mul_f32_e32 v60, v60, v238
	v_mul_f32_e32 v61, v61, v239
	v_mul_f32_e32 v62, v62, v240
	v_mul_f32_e32 v63, v63, v241
	v_mul_f32_e32 v56, v56, v242
	v_mul_f32_e32 v57, v57, v243
	v_mul_f32_e32 v58, v58, v244
	v_mul_f32_e32 v59, v59, v245
	v_cvt_pk_bf16_f32 v48, v60, v61
	v_cvt_pk_bf16_f32 v49, v62, v63
	v_cvt_pk_bf16_f32 v50, v56, v57
	v_cvt_pk_bf16_f32 v51, v58, v59
	global_store_dwordx4 v[246:247], v[48:51], off nt
	v_lshl_add_u64 v[246:247], v[246:247], 0, s[98:99]
	v_fma_f32 v44, v44, v235, v160
	v_fma_f32 v45, v45, v235, v161
	v_fma_f32 v46, v46, v235, v162
	v_fma_f32 v47, v47, v235, v163
	v_fma_f32 v40, v40, v235, v168
	v_fma_f32 v41, v41, v235, v169
	v_fma_f32 v42, v42, v235, v170
	v_fma_f32 v43, v43, v235, v171
	v_mul_f32_e32 v238, 0xbfb8aa3b, v44
	v_mul_f32_e32 v239, 0xbfb8aa3b, v45
	v_mul_f32_e32 v240, 0xbfb8aa3b, v46
	v_mul_f32_e32 v241, 0xbfb8aa3b, v47
	v_mul_f32_e32 v242, 0xbfb8aa3b, v40
	v_mul_f32_e32 v243, 0xbfb8aa3b, v41
	v_mul_f32_e32 v244, 0xbfb8aa3b, v42
	v_mul_f32_e32 v245, 0xbfb8aa3b, v43
	v_exp_f32_e32 v238, v238
	v_exp_f32_e32 v239, v239
	v_exp_f32_e32 v240, v240
	v_exp_f32_e32 v241, v241
	v_exp_f32_e32 v242, v242
	v_exp_f32_e32 v243, v243
	v_exp_f32_e32 v244, v244
	v_exp_f32_e32 v245, v245
	v_fma_f32 v36, v36, v235, v156
	v_fma_f32 v37, v37, v235, v157
	v_fma_f32 v38, v38, v235, v158
	v_fma_f32 v39, v39, v235, v159
	v_fma_f32 v32, v32, v235, v164
	v_fma_f32 v33, v33, v235, v165
	v_fma_f32 v34, v34, v235, v166
	v_fma_f32 v35, v35, v235, v167
	v_add_f32_e32 v238, 1.0, v238
	v_add_f32_e32 v239, 1.0, v239
	v_add_f32_e32 v240, 1.0, v240
	v_add_f32_e32 v241, 1.0, v241
	v_add_f32_e32 v242, 1.0, v242
	v_add_f32_e32 v243, 1.0, v243
	v_add_f32_e32 v244, 1.0, v244
	v_add_f32_e32 v245, 1.0, v245
	v_rcp_f32_e32 v238, v238
	v_rcp_f32_e32 v239, v239
	v_rcp_f32_e32 v240, v240
	v_rcp_f32_e32 v241, v241
	v_rcp_f32_e32 v242, v242
	v_rcp_f32_e32 v243, v243
	v_rcp_f32_e32 v244, v244
	v_rcp_f32_e32 v245, v245
	v_mul_f32_e32 v44, v44, v36
	v_mul_f32_e32 v45, v45, v37
	v_mul_f32_e32 v46, v46, v38
	v_mul_f32_e32 v47, v47, v39
	v_mul_f32_e32 v40, v40, v32
	v_mul_f32_e32 v41, v41, v33
	v_mul_f32_e32 v42, v42, v34
	v_mul_f32_e32 v43, v43, v35
	v_mul_f32_e32 v44, v44, v238
	v_mul_f32_e32 v45, v45, v239
	v_mul_f32_e32 v46, v46, v240
	v_mul_f32_e32 v47, v47, v241
	v_mul_f32_e32 v40, v40, v242
	v_mul_f32_e32 v41, v41, v243
	v_mul_f32_e32 v42, v42, v244
	v_mul_f32_e32 v43, v43, v245
	v_cvt_pk_bf16_f32 v32, v44, v45
	v_cvt_pk_bf16_f32 v33, v46, v47
	v_cvt_pk_bf16_f32 v34, v40, v41
	v_cvt_pk_bf16_f32 v35, v42, v43
	global_store_dwordx4 v[246:247], v[32:35], off nt
	v_lshl_add_u64 v[246:247], v[246:247], 0, s[98:99]
	v_fma_f32 v28, v28, v236, v160
	v_fma_f32 v29, v29, v236, v161
	v_fma_f32 v30, v30, v236, v162
	v_fma_f32 v31, v31, v236, v163
	v_fma_f32 v24, v24, v236, v168
	v_fma_f32 v25, v25, v236, v169
	v_fma_f32 v26, v26, v236, v170
	v_fma_f32 v27, v27, v236, v171
	v_mul_f32_e32 v238, 0xbfb8aa3b, v28
	v_mul_f32_e32 v239, 0xbfb8aa3b, v29
	v_mul_f32_e32 v240, 0xbfb8aa3b, v30
	v_mul_f32_e32 v241, 0xbfb8aa3b, v31
	v_mul_f32_e32 v242, 0xbfb8aa3b, v24
	v_mul_f32_e32 v243, 0xbfb8aa3b, v25
	v_mul_f32_e32 v244, 0xbfb8aa3b, v26
	v_mul_f32_e32 v245, 0xbfb8aa3b, v27
	v_exp_f32_e32 v238, v238
	v_exp_f32_e32 v239, v239
	v_exp_f32_e32 v240, v240
	v_exp_f32_e32 v241, v241
	v_exp_f32_e32 v242, v242
	v_exp_f32_e32 v243, v243
	v_exp_f32_e32 v244, v244
	v_exp_f32_e32 v245, v245
	v_fma_f32 v20, v20, v236, v156
	v_fma_f32 v21, v21, v236, v157
	v_fma_f32 v22, v22, v236, v158
	v_fma_f32 v23, v23, v236, v159
	v_fma_f32 v16, v16, v236, v164
	v_fma_f32 v17, v17, v236, v165
	v_fma_f32 v18, v18, v236, v166
	v_fma_f32 v19, v19, v236, v167
	v_add_f32_e32 v238, 1.0, v238
	v_add_f32_e32 v239, 1.0, v239
	v_add_f32_e32 v240, 1.0, v240
	v_add_f32_e32 v241, 1.0, v241
	v_add_f32_e32 v242, 1.0, v242
	v_add_f32_e32 v243, 1.0, v243
	v_add_f32_e32 v244, 1.0, v244
	v_add_f32_e32 v245, 1.0, v245
	v_rcp_f32_e32 v238, v238
	v_rcp_f32_e32 v239, v239
	v_rcp_f32_e32 v240, v240
	v_rcp_f32_e32 v241, v241
	v_rcp_f32_e32 v242, v242
	v_rcp_f32_e32 v243, v243
	v_rcp_f32_e32 v244, v244
	v_rcp_f32_e32 v245, v245
	v_mul_f32_e32 v28, v28, v20
	v_mul_f32_e32 v29, v29, v21
	v_mul_f32_e32 v30, v30, v22
	v_mul_f32_e32 v31, v31, v23
	v_mul_f32_e32 v24, v24, v16
	v_mul_f32_e32 v25, v25, v17
	v_mul_f32_e32 v26, v26, v18
	v_mul_f32_e32 v27, v27, v19
	v_mul_f32_e32 v28, v28, v238
	v_mul_f32_e32 v29, v29, v239
	v_mul_f32_e32 v30, v30, v240
	v_mul_f32_e32 v31, v31, v241
	v_mul_f32_e32 v24, v24, v242
	v_mul_f32_e32 v25, v25, v243
	v_mul_f32_e32 v26, v26, v244
	v_mul_f32_e32 v27, v27, v245
	v_cvt_pk_bf16_f32 v16, v28, v29
	v_cvt_pk_bf16_f32 v17, v30, v31
	v_cvt_pk_bf16_f32 v18, v24, v25
	v_cvt_pk_bf16_f32 v19, v26, v27
	global_store_dwordx4 v[246:247], v[16:19], off nt
	v_lshl_add_u64 v[246:247], v[246:247], 0, s[98:99]
	v_fma_f32 v12, v12, v237, v160
	v_fma_f32 v13, v13, v237, v161
	v_fma_f32 v14, v14, v237, v162
	v_fma_f32 v15, v15, v237, v163
	v_fma_f32 v8, v8, v237, v168
	v_fma_f32 v9, v9, v237, v169
	v_fma_f32 v10, v10, v237, v170
	v_fma_f32 v11, v11, v237, v171
	v_mul_f32_e32 v238, 0xbfb8aa3b, v12
	v_mul_f32_e32 v239, 0xbfb8aa3b, v13
	v_mul_f32_e32 v240, 0xbfb8aa3b, v14
	v_mul_f32_e32 v241, 0xbfb8aa3b, v15
	v_mul_f32_e32 v242, 0xbfb8aa3b, v8
	v_mul_f32_e32 v243, 0xbfb8aa3b, v9
	v_mul_f32_e32 v244, 0xbfb8aa3b, v10
	v_mul_f32_e32 v245, 0xbfb8aa3b, v11
	v_exp_f32_e32 v238, v238
	v_exp_f32_e32 v239, v239
	v_exp_f32_e32 v240, v240
	v_exp_f32_e32 v241, v241
	v_exp_f32_e32 v242, v242
	v_exp_f32_e32 v243, v243
	v_exp_f32_e32 v244, v244
	v_exp_f32_e32 v245, v245
	v_fma_f32 v4, v4, v237, v156
	v_fma_f32 v5, v5, v237, v157
	v_fma_f32 v6, v6, v237, v158
	v_fma_f32 v7, v7, v237, v159
	v_fma_f32 v0, v0, v237, v164
	v_fma_f32 v1, v1, v237, v165
	v_fma_f32 v2, v2, v237, v166
	v_fma_f32 v3, v3, v237, v167
	v_add_f32_e32 v238, 1.0, v238
	v_add_f32_e32 v239, 1.0, v239
	v_add_f32_e32 v240, 1.0, v240
	v_add_f32_e32 v241, 1.0, v241
	v_add_f32_e32 v242, 1.0, v242
	v_add_f32_e32 v243, 1.0, v243
	v_add_f32_e32 v244, 1.0, v244
	v_add_f32_e32 v245, 1.0, v245
	v_rcp_f32_e32 v238, v238
	v_rcp_f32_e32 v239, v239
	v_rcp_f32_e32 v240, v240
	v_rcp_f32_e32 v241, v241
	v_rcp_f32_e32 v242, v242
	v_rcp_f32_e32 v243, v243
	v_rcp_f32_e32 v244, v244
	v_rcp_f32_e32 v245, v245
	v_mul_f32_e32 v12, v12, v4
	v_mul_f32_e32 v13, v13, v5
	v_mul_f32_e32 v14, v14, v6
	v_mul_f32_e32 v15, v15, v7
	v_mul_f32_e32 v8, v8, v0
	v_mul_f32_e32 v9, v9, v1
	v_mul_f32_e32 v10, v10, v2
	v_mul_f32_e32 v11, v11, v3
	v_mul_f32_e32 v12, v12, v238
	v_mul_f32_e32 v13, v13, v239
	v_mul_f32_e32 v14, v14, v240
	v_mul_f32_e32 v15, v15, v241
	v_mul_f32_e32 v8, v8, v242
	v_mul_f32_e32 v9, v9, v243
	v_mul_f32_e32 v10, v10, v244
	v_mul_f32_e32 v11, v11, v245
	v_cvt_pk_bf16_f32 v0, v12, v13
	v_cvt_pk_bf16_f32 v1, v14, v15
	v_cvt_pk_bf16_f32 v2, v8, v9
	v_cvt_pk_bf16_f32 v3, v10, v11
	s_andn2_b64 vcc, exec, s[0:1]
	s_mov_b64 s[0:1], -1
	global_store_dwordx4 v[246:247], v[0:3], off nt
	s_cbranch_vccnz .LBB0_1118
	s_andn2_b64 vcc, exec, s[10:11]
	s_cbranch_vccnz .LBB0_1117
	s_barrier
	s_branch .LBB0_1117
